# nt (streaming) policy for the 184 MB SwiGLU hidden output stores and the single-use x loads: less last-level-cache pollution; softmax exp guards dropped (bit-exact)
# speedup vs baseline: 1.0078x; 1.0033x over previous
; #define LAS __attribute__((address_space(3)))
; __device__ __forceinline__ unsigned cvt_pk_bf16(float lo, float hi) { f32x2_t v = {lo, hi}; bf16x2_t b = __builtin_convertvector(v, bf16x2_t); return __builtin_bit_cast(unsigned, b); }
; __device__ __forceinline__ float sigm(float x) { return __builtin_amdgcn_rcpf(1.0f + __expf(-x)); }
; __device__ __forceinline__ int opaque_tid() { int t = threadIdx.x; asm volatile("" : "+v"(t)); return t; }
;     __device__ __forceinline__ void operator()(AccRef acc, const pg8::Unit& u, int, int, int, int) const {
;         const int tid = opaque_tid(), wid = __builtin_amdgcn_readfirstlane(tid >> 6), wr = wid >> 2, wc = wid & 3, fr = tid & 15, fq = (tid & 63) >> 4;
;         const int row0 = u.pm * 256 + wr * 64 + fr, col0 = u.pn * 128 + wc * 32 + 8 * fq;
; #pragma unroll
;         for (int ai = 0; ai < 2; ++ai)
; #pragma unroll
;             for (int m = 0; m < 4; ++m) {
;                 const int row = row0 + ai * 128 + m * 16; const float rs = ((const LAS float*)((LAS unsigned char*)g_lds + pg8::RSL_OFF))[wid * 128 + ai * 64 + m * 16 + fr];
;                 float o[8];
; #pragma unroll
;                 for (int n = 0; n < 2; ++n)
; #pragma unroll
;                     for (int j = 0; j < 4; ++j) { const float gv = acc[ai][0][m][n][j] * rs, uv = acc[ai][1][m][n][j] * rs; o[n * 4 + j] = gv * sigm(gv) * uv; }
;                 v4u w; w.x = cvt_pk_bf16(o[0], o[1]); w.y = cvt_pk_bf16(o[2], o[3]); w.z = cvt_pk_bf16(o[4], o[5]); w.w = cvt_pk_bf16(o[6], o[7]);
;                 *(v4u*)(O + (size_t)row * DFFP + col0) = w; }
.LBB0_309:
	v_mov_b32_e32 v140, v155
	s_lshl_b32 s11, s34, 7
	v_readfirstlane_b32 s6, v140
	v_and_b32_e32 v141, 15, v140
	s_ashr_i32 s7, s6, 6
	v_or_b32_e32 v142, s1, v141
	s_lshl_b32 s1, s7, 9
	s_ashr_i32 s6, s6, 2
	v_lshl_add_u32 v141, v141, 2, s1
	s_andn2_b32 s6, s6, 63
	v_add_u32_e32 v149, 0x20000, v141
	v_add_u32_e32 v148, s6, v142
	ds_read2_b32 v[240:241], v149 offset1:16
	ds_read2_b32 v[242:243], v149 offset0:32 offset1:48
	ds_read2_b32 v[244:245], v149 offset0:64 offset1:80
	ds_read2_b32 v[246:247], v149 offset0:96 offset1:112
	s_lshl_b32 s18, s7, 5
	v_readlane_b32 s6, v254, 43
	s_and_b32 s18, s18, 0x60
	v_readlane_b32 s7, v254, 44
	s_or_b32 s11, s18, s11
	v_lshrrev_b32_e32 v140, 1, v140
	s_movk_i32 s1, 0x1600
	v_and_or_b32 v140, v140, 24, s11
	v_mov_b32_e32 v150, 1.0
	v_ashrrev_i32_e32 v141, 31, v140
	v_mov_b64_e32 v[142:143], s[6:7]
	v_lshlrev_b64 v[140:141], 1, v[140:141]
	v_mad_i64_i32 v[252:253], s[6:7], v148, s1, v[142:143]
	v_lshl_add_u64 v[252:253], v[252:253], 0, v[140:141]
	s_waitcnt lgkmcnt(0)
	v_mul_f32_e32 v248, 0xbfb8aa3b, v240
	v_mul_f32_e32 v250, v240, v240
	v_pk_mul_f32 v[122:123], v[122:123], v[126:127]
	v_pk_mul_f32 v[124:125], v[124:125], v[128:129]
	v_pk_mul_f32 v[114:115], v[114:115], v[118:119]
	v_pk_mul_f32 v[116:117], v[116:117], v[120:121]
	v_pk_mul_f32 v[126:127], v[126:127], v[248:249] op_sel_hi:[1,0]
	v_pk_mul_f32 v[128:129], v[128:129], v[248:249] op_sel_hi:[1,0]
	v_pk_mul_f32 v[118:119], v[118:119], v[248:249] op_sel_hi:[1,0]
	v_pk_mul_f32 v[120:121], v[120:121], v[248:249] op_sel_hi:[1,0]
	v_exp_f32_e32 v126, v126
	v_exp_f32_e32 v127, v127
	v_exp_f32_e32 v128, v128
	v_exp_f32_e32 v129, v129
	v_exp_f32_e32 v118, v118
	v_exp_f32_e32 v119, v119
	v_exp_f32_e32 v120, v120
	v_exp_f32_e32 v121, v121
	v_pk_mul_f32 v[122:123], v[122:123], v[250:251] op_sel_hi:[1,0]
	v_pk_mul_f32 v[124:125], v[124:125], v[250:251] op_sel_hi:[1,0]
	v_pk_mul_f32 v[114:115], v[114:115], v[250:251] op_sel_hi:[1,0]
	v_pk_mul_f32 v[116:117], v[116:117], v[250:251] op_sel_hi:[1,0]
	v_pk_add_f32 v[126:127], v[126:127], v[150:151] op_sel_hi:[1,0]
	v_pk_add_f32 v[128:129], v[128:129], v[150:151] op_sel_hi:[1,0]
	v_pk_add_f32 v[118:119], v[118:119], v[150:151] op_sel_hi:[1,0]
	v_pk_add_f32 v[120:121], v[120:121], v[150:151] op_sel_hi:[1,0]
	v_rcp_f32_e32 v126, v126
	v_rcp_f32_e32 v127, v127
	v_rcp_f32_e32 v128, v128
	v_rcp_f32_e32 v129, v129
	v_rcp_f32_e32 v118, v118
	v_rcp_f32_e32 v119, v119
	v_rcp_f32_e32 v120, v120
	v_rcp_f32_e32 v121, v121
	v_pk_mul_f32 v[122:123], v[122:123], v[126:127]
	v_pk_mul_f32 v[124:125], v[124:125], v[128:129]
	v_pk_mul_f32 v[114:115], v[114:115], v[118:119]
	v_pk_mul_f32 v[116:117], v[116:117], v[120:121]
	v_cvt_pk_bf16_f32 v232, v122, v123
	v_cvt_pk_bf16_f32 v233, v124, v125
	v_cvt_pk_bf16_f32 v234, v114, v115
	v_cvt_pk_bf16_f32 v235, v116, v117
	global_store_dwordx4 v[252:253], v[232:235], off nt
	v_add_co_u32_e32 v252, vcc, 0x16000, v252
	s_nop 1
	v_addc_co_u32_e32 v253, vcc, 0, v253, vcc
	v_mul_f32_e32 v248, 0xbfb8aa3b, v241
	v_mul_f32_e32 v250, v241, v241
	v_pk_mul_f32 v[106:107], v[106:107], v[110:111]
	v_pk_mul_f32 v[108:109], v[108:109], v[112:113]
	v_pk_mul_f32 v[98:99], v[98:99], v[102:103]
	v_pk_mul_f32 v[100:101], v[100:101], v[104:105]
	v_pk_mul_f32 v[110:111], v[110:111], v[248:249] op_sel_hi:[1,0]
	v_pk_mul_f32 v[112:113], v[112:113], v[248:249] op_sel_hi:[1,0]
	v_pk_mul_f32 v[102:103], v[102:103], v[248:249] op_sel_hi:[1,0]
	v_pk_mul_f32 v[104:105], v[104:105], v[248:249] op_sel_hi:[1,0]
	v_exp_f32_e32 v110, v110
	v_exp_f32_e32 v111, v111
	v_exp_f32_e32 v112, v112
	v_exp_f32_e32 v113, v113
	v_exp_f32_e32 v102, v102
	v_exp_f32_e32 v103, v103
	v_exp_f32_e32 v104, v104
	v_exp_f32_e32 v105, v105
	v_pk_mul_f32 v[106:107], v[106:107], v[250:251] op_sel_hi:[1,0]
	v_pk_mul_f32 v[108:109], v[108:109], v[250:251] op_sel_hi:[1,0]
	v_pk_mul_f32 v[98:99], v[98:99], v[250:251] op_sel_hi:[1,0]
	v_pk_mul_f32 v[100:101], v[100:101], v[250:251] op_sel_hi:[1,0]
	v_pk_add_f32 v[110:111], v[110:111], v[150:151] op_sel_hi:[1,0]
	v_pk_add_f32 v[112:113], v[112:113], v[150:151] op_sel_hi:[1,0]
	v_pk_add_f32 v[102:103], v[102:103], v[150:151] op_sel_hi:[1,0]
	v_pk_add_f32 v[104:105], v[104:105], v[150:151] op_sel_hi:[1,0]
	v_rcp_f32_e32 v110, v110
	v_rcp_f32_e32 v111, v111
	v_rcp_f32_e32 v112, v112
	v_rcp_f32_e32 v113, v113
	v_rcp_f32_e32 v102, v102
	v_rcp_f32_e32 v103, v103
	v_rcp_f32_e32 v104, v104
	v_rcp_f32_e32 v105, v105
	v_pk_mul_f32 v[106:107], v[106:107], v[110:111]
	v_pk_mul_f32 v[108:109], v[108:109], v[112:113]
	v_pk_mul_f32 v[98:99], v[98:99], v[102:103]
	v_pk_mul_f32 v[100:101], v[100:101], v[104:105]
	v_cvt_pk_bf16_f32 v236, v106, v107
	v_cvt_pk_bf16_f32 v237, v108, v109
	v_cvt_pk_bf16_f32 v238, v98, v99
	v_cvt_pk_bf16_f32 v239, v100, v101
	global_store_dwordx4 v[252:253], v[236:239], off nt
	v_add_co_u32_e32 v252, vcc, 0x16000, v252
	s_nop 1
	v_addc_co_u32_e32 v253, vcc, 0, v253, vcc
	v_mul_f32_e32 v248, 0xbfb8aa3b, v242
	v_mul_f32_e32 v250, v242, v242
	v_pk_mul_f32 v[90:91], v[90:91], v[94:95]
	v_pk_mul_f32 v[92:93], v[92:93], v[96:97]
	v_pk_mul_f32 v[82:83], v[82:83], v[86:87]
	v_pk_mul_f32 v[84:85], v[84:85], v[88:89]
	v_pk_mul_f32 v[94:95], v[94:95], v[248:249] op_sel_hi:[1,0]
	v_pk_mul_f32 v[96:97], v[96:97], v[248:249] op_sel_hi:[1,0]
	v_pk_mul_f32 v[86:87], v[86:87], v[248:249] op_sel_hi:[1,0]
	v_pk_mul_f32 v[88:89], v[88:89], v[248:249] op_sel_hi:[1,0]
	v_exp_f32_e32 v94, v94
	v_exp_f32_e32 v95, v95
	v_exp_f32_e32 v96, v96
	v_exp_f32_e32 v97, v97
	v_exp_f32_e32 v86, v86
	v_exp_f32_e32 v87, v87
	v_exp_f32_e32 v88, v88
	v_exp_f32_e32 v89, v89
	v_pk_mul_f32 v[90:91], v[90:91], v[250:251] op_sel_hi:[1,0]
; #define LAS __attribute__((address_space(3)))
; __device__ __forceinline__ unsigned cvt_pk_bf16(float lo, float hi) { f32x2_t v = {lo, hi}; bf16x2_t b = __builtin_convertvector(v, bf16x2_t); return __builtin_bit_cast(unsigned, b); }
; __device__ __forceinline__ float sigm(float x) { return __builtin_amdgcn_rcpf(1.0f + __expf(-x)); }
;     __device__ __forceinline__ void operator()(AccRef acc, const pg8::Unit& u, int, int, int, int) const {
;     ...
;                 const int row = row0 + ai * 128 + m * 16; const float rs = ((const LAS float*)((LAS unsigned char*)g_lds + pg8::RSL_OFF))[wid * 128 + ai * 64 + m * 16 + fr];
;                 float o[8];
; #pragma unroll
;                 for (int n = 0; n < 2; ++n)
; #pragma unroll
;                     for (int j = 0; j < 4; ++j) { const float gv = acc[ai][0][m][n][j] * rs, uv = acc[ai][1][m][n][j] * rs; o[n * 4 + j] = gv * sigm(gv) * uv; }
;                 v4u w; w.x = cvt_pk_bf16(o[0], o[1]); w.y = cvt_pk_bf16(o[2], o[3]); w.z = cvt_pk_bf16(o[4], o[5]); w.w = cvt_pk_bf16(o[6], o[7]);
;                 *(v4u*)(O + (size_t)row * DFFP + col0) = w; }
	v_pk_mul_f32 v[92:93], v[92:93], v[250:251] op_sel_hi:[1,0]
	v_pk_mul_f32 v[82:83], v[82:83], v[250:251] op_sel_hi:[1,0]
	v_pk_mul_f32 v[84:85], v[84:85], v[250:251] op_sel_hi:[1,0]
	v_pk_add_f32 v[94:95], v[94:95], v[150:151] op_sel_hi:[1,0]
	v_pk_add_f32 v[96:97], v[96:97], v[150:151] op_sel_hi:[1,0]
	v_pk_add_f32 v[86:87], v[86:87], v[150:151] op_sel_hi:[1,0]
	v_pk_add_f32 v[88:89], v[88:89], v[150:151] op_sel_hi:[1,0]
	v_rcp_f32_e32 v94, v94
	v_rcp_f32_e32 v95, v95
	v_rcp_f32_e32 v96, v96
	v_rcp_f32_e32 v97, v97
	v_rcp_f32_e32 v86, v86
	v_rcp_f32_e32 v87, v87
	v_rcp_f32_e32 v88, v88
	v_rcp_f32_e32 v89, v89
	v_pk_mul_f32 v[90:91], v[90:91], v[94:95]
	v_pk_mul_f32 v[92:93], v[92:93], v[96:97]
	v_pk_mul_f32 v[82:83], v[82:83], v[86:87]
	v_pk_mul_f32 v[84:85], v[84:85], v[88:89]
	v_cvt_pk_bf16_f32 v232, v90, v91
	v_cvt_pk_bf16_f32 v233, v92, v93
	v_cvt_pk_bf16_f32 v234, v82, v83
	v_cvt_pk_bf16_f32 v235, v84, v85
	global_store_dwordx4 v[252:253], v[232:235], off nt
	v_add_co_u32_e32 v252, vcc, 0x16000, v252
	s_nop 1
	v_addc_co_u32_e32 v253, vcc, 0, v253, vcc
	v_mul_f32_e32 v248, 0xbfb8aa3b, v243
	v_mul_f32_e32 v250, v243, v243
	v_pk_mul_f32 v[74:75], v[74:75], v[78:79]
	v_pk_mul_f32 v[76:77], v[76:77], v[80:81]
	v_pk_mul_f32 v[66:67], v[66:67], v[70:71]
	v_pk_mul_f32 v[68:69], v[68:69], v[72:73]
	v_pk_mul_f32 v[78:79], v[78:79], v[248:249] op_sel_hi:[1,0]
	v_pk_mul_f32 v[80:81], v[80:81], v[248:249] op_sel_hi:[1,0]
	v_pk_mul_f32 v[70:71], v[70:71], v[248:249] op_sel_hi:[1,0]
	v_pk_mul_f32 v[72:73], v[72:73], v[248:249] op_sel_hi:[1,0]
	v_exp_f32_e32 v78, v78
	v_exp_f32_e32 v79, v79
	v_exp_f32_e32 v80, v80
	v_exp_f32_e32 v81, v81
	v_exp_f32_e32 v70, v70
	v_exp_f32_e32 v71, v71
	v_exp_f32_e32 v72, v72
	v_exp_f32_e32 v73, v73
	v_pk_mul_f32 v[74:75], v[74:75], v[250:251] op_sel_hi:[1,0]
	v_pk_mul_f32 v[76:77], v[76:77], v[250:251] op_sel_hi:[1,0]
	v_pk_mul_f32 v[66:67], v[66:67], v[250:251] op_sel_hi:[1,0]
	v_pk_mul_f32 v[68:69], v[68:69], v[250:251] op_sel_hi:[1,0]
	v_pk_add_f32 v[78:79], v[78:79], v[150:151] op_sel_hi:[1,0]
	v_pk_add_f32 v[80:81], v[80:81], v[150:151] op_sel_hi:[1,0]
	v_pk_add_f32 v[70:71], v[70:71], v[150:151] op_sel_hi:[1,0]
	v_pk_add_f32 v[72:73], v[72:73], v[150:151] op_sel_hi:[1,0]
	v_rcp_f32_e32 v78, v78
	v_rcp_f32_e32 v79, v79
	v_rcp_f32_e32 v80, v80
	v_rcp_f32_e32 v81, v81
	v_rcp_f32_e32 v70, v70
	v_rcp_f32_e32 v71, v71
	v_rcp_f32_e32 v72, v72
	v_rcp_f32_e32 v73, v73
	v_pk_mul_f32 v[74:75], v[74:75], v[78:79]
	v_pk_mul_f32 v[76:77], v[76:77], v[80:81]
	v_pk_mul_f32 v[66:67], v[66:67], v[70:71]
	v_pk_mul_f32 v[68:69], v[68:69], v[72:73]
	v_cvt_pk_bf16_f32 v236, v74, v75
	v_cvt_pk_bf16_f32 v237, v76, v77
	v_cvt_pk_bf16_f32 v238, v66, v67
	v_cvt_pk_bf16_f32 v239, v68, v69
	global_store_dwordx4 v[252:253], v[236:239], off nt
	v_add_co_u32_e32 v252, vcc, 0x6e000, v252
	s_nop 1
	v_addc_co_u32_e32 v253, vcc, 0, v253, vcc
	v_mul_f32_e32 v248, 0xbfb8aa3b, v244
	v_mul_f32_e32 v250, v244, v244
	v_pk_mul_f32 v[58:59], v[58:59], v[62:63]
	v_pk_mul_f32 v[60:61], v[60:61], v[64:65]
	v_pk_mul_f32 v[50:51], v[50:51], v[54:55]
	v_pk_mul_f32 v[52:53], v[52:53], v[56:57]
	v_pk_mul_f32 v[62:63], v[62:63], v[248:249] op_sel_hi:[1,0]
	v_pk_mul_f32 v[64:65], v[64:65], v[248:249] op_sel_hi:[1,0]
	v_pk_mul_f32 v[54:55], v[54:55], v[248:249] op_sel_hi:[1,0]
	v_pk_mul_f32 v[56:57], v[56:57], v[248:249] op_sel_hi:[1,0]
	v_exp_f32_e32 v62, v62
	v_exp_f32_e32 v63, v63
	v_exp_f32_e32 v64, v64
	v_exp_f32_e32 v65, v65
	v_exp_f32_e32 v54, v54
	v_exp_f32_e32 v55, v55
	v_exp_f32_e32 v56, v56
	v_exp_f32_e32 v57, v57
	v_pk_mul_f32 v[58:59], v[58:59], v[250:251] op_sel_hi:[1,0]
	v_pk_mul_f32 v[60:61], v[60:61], v[250:251] op_sel_hi:[1,0]
	v_pk_mul_f32 v[50:51], v[50:51], v[250:251] op_sel_hi:[1,0]
	v_pk_mul_f32 v[52:53], v[52:53], v[250:251] op_sel_hi:[1,0]
	v_pk_add_f32 v[62:63], v[62:63], v[150:151] op_sel_hi:[1,0]
	v_pk_add_f32 v[64:65], v[64:65], v[150:151] op_sel_hi:[1,0]
	v_pk_add_f32 v[54:55], v[54:55], v[150:151] op_sel_hi:[1,0]
	v_pk_add_f32 v[56:57], v[56:57], v[150:151] op_sel_hi:[1,0]
	v_rcp_f32_e32 v62, v62
	v_rcp_f32_e32 v63, v63
	v_rcp_f32_e32 v64, v64
	v_rcp_f32_e32 v65, v65
	v_rcp_f32_e32 v54, v54
	v_rcp_f32_e32 v55, v55
	v_rcp_f32_e32 v56, v56
	v_rcp_f32_e32 v57, v57
	v_pk_mul_f32 v[58:59], v[58:59], v[62:63]
	v_pk_mul_f32 v[60:61], v[60:61], v[64:65]
	v_pk_mul_f32 v[50:51], v[50:51], v[54:55]
	v_pk_mul_f32 v[52:53], v[52:53], v[56:57]
	v_cvt_pk_bf16_f32 v232, v58, v59
	v_cvt_pk_bf16_f32 v233, v60, v61
	v_cvt_pk_bf16_f32 v234, v50, v51
	v_cvt_pk_bf16_f32 v235, v52, v53
	global_store_dwordx4 v[252:253], v[232:235], off nt
	v_add_co_u32_e32 v252, vcc, 0x16000, v252
	s_nop 1
	v_addc_co_u32_e32 v253, vcc, 0, v253, vcc
	v_mul_f32_e32 v248, 0xbfb8aa3b, v245
	v_mul_f32_e32 v250, v245, v245
	v_pk_mul_f32 v[42:43], v[42:43], v[46:47]
	v_pk_mul_f32 v[44:45], v[44:45], v[48:49]
	v_pk_mul_f32 v[34:35], v[34:35], v[38:39]
	v_pk_mul_f32 v[36:37], v[36:37], v[40:41]
	v_pk_mul_f32 v[46:47], v[46:47], v[248:249] op_sel_hi:[1,0]
	v_pk_mul_f32 v[48:49], v[48:49], v[248:249] op_sel_hi:[1,0]
; #define LAS __attribute__((address_space(3)))
; __device__ __forceinline__ unsigned cvt_pk_bf16(float lo, float hi) { f32x2_t v = {lo, hi}; bf16x2_t b = __builtin_convertvector(v, bf16x2_t); return __builtin_bit_cast(unsigned, b); }
; __device__ __forceinline__ float sigm(float x) { return __builtin_amdgcn_rcpf(1.0f + __expf(-x)); }
; #define PG8_BAR __builtin_amdgcn_s_barrier()
; template <class Epi, bool ALIGN_EPI>
; __device__ __forceinline__ void gemm_phase(LAS unsigned char* lds, const Gemm g, const StaticOrder& S, const Epi& E) {
;     ...
;         if (!has_next) break;
; #pragma unroll
;         for (int a = 0; a < 2; ++a)
; #pragma unroll
;             for (int b = 0; b < 2; ++b)
; #pragma unroll
;                 for (int m = 0; m < 4; ++m)
; #pragma unroll
;                     for (int n = 0; n < 2; ++n) acc[a][b][m][n] = (f32x4){0.f, 0.f, 0.f, 0.f};
;         cur = nxt; cA = nA; cB = nB; ++ui;
;         if constexpr (ALIGN_EPI) { if (wr == 1) PG8_BAR; }
;     __device__ __forceinline__ void operator()(AccRef acc, const pg8::Unit& u, int, int, int, int) const {
;     ...
;                 const int row = row0 + ai * 128 + m * 16; const float rs = ((const LAS float*)((LAS unsigned char*)g_lds + pg8::RSL_OFF))[wid * 128 + ai * 64 + m * 16 + fr];
;                 float o[8];
; #pragma unroll
;                 for (int n = 0; n < 2; ++n)
; #pragma unroll
;                     for (int j = 0; j < 4; ++j) { const float gv = acc[ai][0][m][n][j] * rs, uv = acc[ai][1][m][n][j] * rs; o[n * 4 + j] = gv * sigm(gv) * uv; }
;                 v4u w; w.x = cvt_pk_bf16(o[0], o[1]); w.y = cvt_pk_bf16(o[2], o[3]); w.z = cvt_pk_bf16(o[4], o[5]); w.w = cvt_pk_bf16(o[6], o[7]);
;                 *(v4u*)(O + (size_t)row * DFFP + col0) = w; }
	v_pk_mul_f32 v[38:39], v[38:39], v[248:249] op_sel_hi:[1,0]
	v_pk_mul_f32 v[40:41], v[40:41], v[248:249] op_sel_hi:[1,0]
	v_exp_f32_e32 v46, v46
	v_exp_f32_e32 v47, v47
	v_exp_f32_e32 v48, v48
	v_exp_f32_e32 v49, v49
	v_exp_f32_e32 v38, v38
	v_exp_f32_e32 v39, v39
	v_exp_f32_e32 v40, v40
	v_exp_f32_e32 v41, v41
	v_pk_mul_f32 v[42:43], v[42:43], v[250:251] op_sel_hi:[1,0]
	v_pk_mul_f32 v[44:45], v[44:45], v[250:251] op_sel_hi:[1,0]
	v_pk_mul_f32 v[34:35], v[34:35], v[250:251] op_sel_hi:[1,0]
	v_pk_mul_f32 v[36:37], v[36:37], v[250:251] op_sel_hi:[1,0]
	v_pk_add_f32 v[46:47], v[46:47], v[150:151] op_sel_hi:[1,0]
	v_pk_add_f32 v[48:49], v[48:49], v[150:151] op_sel_hi:[1,0]
	v_pk_add_f32 v[38:39], v[38:39], v[150:151] op_sel_hi:[1,0]
	v_pk_add_f32 v[40:41], v[40:41], v[150:151] op_sel_hi:[1,0]
	v_rcp_f32_e32 v46, v46
	v_rcp_f32_e32 v47, v47
	v_rcp_f32_e32 v48, v48
	v_rcp_f32_e32 v49, v49
	v_rcp_f32_e32 v38, v38
	v_rcp_f32_e32 v39, v39
	v_rcp_f32_e32 v40, v40
	v_rcp_f32_e32 v41, v41
	v_pk_mul_f32 v[42:43], v[42:43], v[46:47]
	v_pk_mul_f32 v[44:45], v[44:45], v[48:49]
	v_pk_mul_f32 v[34:35], v[34:35], v[38:39]
	v_pk_mul_f32 v[36:37], v[36:37], v[40:41]
	v_cvt_pk_bf16_f32 v236, v42, v43
	v_cvt_pk_bf16_f32 v237, v44, v45
	v_cvt_pk_bf16_f32 v238, v34, v35
	v_cvt_pk_bf16_f32 v239, v36, v37
	global_store_dwordx4 v[252:253], v[236:239], off nt
	v_add_co_u32_e32 v252, vcc, 0x16000, v252
	s_nop 1
	v_addc_co_u32_e32 v253, vcc, 0, v253, vcc
	v_mul_f32_e32 v248, 0xbfb8aa3b, v246
	v_mul_f32_e32 v250, v246, v246
	v_pk_mul_f32 v[26:27], v[26:27], v[30:31]
	v_pk_mul_f32 v[28:29], v[28:29], v[32:33]
	v_pk_mul_f32 v[18:19], v[18:19], v[22:23]
	v_pk_mul_f32 v[20:21], v[20:21], v[24:25]
	v_pk_mul_f32 v[30:31], v[30:31], v[248:249] op_sel_hi:[1,0]
	v_pk_mul_f32 v[32:33], v[32:33], v[248:249] op_sel_hi:[1,0]
	v_pk_mul_f32 v[22:23], v[22:23], v[248:249] op_sel_hi:[1,0]
	v_pk_mul_f32 v[24:25], v[24:25], v[248:249] op_sel_hi:[1,0]
	v_exp_f32_e32 v30, v30
	v_exp_f32_e32 v31, v31
	v_exp_f32_e32 v32, v32
	v_exp_f32_e32 v33, v33
	v_exp_f32_e32 v22, v22
	v_exp_f32_e32 v23, v23
	v_exp_f32_e32 v24, v24
	v_exp_f32_e32 v25, v25
	v_pk_mul_f32 v[26:27], v[26:27], v[250:251] op_sel_hi:[1,0]
	v_pk_mul_f32 v[28:29], v[28:29], v[250:251] op_sel_hi:[1,0]
	v_pk_mul_f32 v[18:19], v[18:19], v[250:251] op_sel_hi:[1,0]
	v_pk_mul_f32 v[20:21], v[20:21], v[250:251] op_sel_hi:[1,0]
	v_pk_add_f32 v[30:31], v[30:31], v[150:151] op_sel_hi:[1,0]
	v_pk_add_f32 v[32:33], v[32:33], v[150:151] op_sel_hi:[1,0]
	v_pk_add_f32 v[22:23], v[22:23], v[150:151] op_sel_hi:[1,0]
	v_pk_add_f32 v[24:25], v[24:25], v[150:151] op_sel_hi:[1,0]
	v_rcp_f32_e32 v30, v30
	v_rcp_f32_e32 v31, v31
	v_rcp_f32_e32 v32, v32
	v_rcp_f32_e32 v33, v33
	v_rcp_f32_e32 v22, v22
	v_rcp_f32_e32 v23, v23
	v_rcp_f32_e32 v24, v24
	v_rcp_f32_e32 v25, v25
	v_pk_mul_f32 v[26:27], v[26:27], v[30:31]
	v_pk_mul_f32 v[28:29], v[28:29], v[32:33]
	v_pk_mul_f32 v[18:19], v[18:19], v[22:23]
	v_pk_mul_f32 v[20:21], v[20:21], v[24:25]
	v_cvt_pk_bf16_f32 v232, v26, v27
	v_cvt_pk_bf16_f32 v233, v28, v29
	v_cvt_pk_bf16_f32 v234, v18, v19
	v_cvt_pk_bf16_f32 v235, v20, v21
	global_store_dwordx4 v[252:253], v[232:235], off nt
	v_add_co_u32_e32 v252, vcc, 0x16000, v252
	s_nop 1
	v_addc_co_u32_e32 v253, vcc, 0, v253, vcc
	v_mul_f32_e32 v248, 0xbfb8aa3b, v247
	v_mul_f32_e32 v250, v247, v247
	v_pk_mul_f32 v[10:11], v[10:11], v[14:15]
	v_pk_mul_f32 v[12:13], v[12:13], v[16:17]
	v_pk_mul_f32 v[2:3], v[2:3], v[6:7]
	v_pk_mul_f32 v[4:5], v[4:5], v[8:9]
	v_pk_mul_f32 v[14:15], v[14:15], v[248:249] op_sel_hi:[1,0]
	v_pk_mul_f32 v[16:17], v[16:17], v[248:249] op_sel_hi:[1,0]
	v_pk_mul_f32 v[6:7], v[6:7], v[248:249] op_sel_hi:[1,0]
	v_pk_mul_f32 v[8:9], v[8:9], v[248:249] op_sel_hi:[1,0]
	v_exp_f32_e32 v14, v14
	v_exp_f32_e32 v15, v15
	v_exp_f32_e32 v16, v16
	v_exp_f32_e32 v17, v17
	v_exp_f32_e32 v6, v6
	v_exp_f32_e32 v7, v7
	v_exp_f32_e32 v8, v8
	v_exp_f32_e32 v9, v9
	v_pk_mul_f32 v[10:11], v[10:11], v[250:251] op_sel_hi:[1,0]
	v_pk_mul_f32 v[12:13], v[12:13], v[250:251] op_sel_hi:[1,0]
	v_pk_mul_f32 v[2:3], v[2:3], v[250:251] op_sel_hi:[1,0]
	v_pk_mul_f32 v[4:5], v[4:5], v[250:251] op_sel_hi:[1,0]
	v_pk_add_f32 v[14:15], v[14:15], v[150:151] op_sel_hi:[1,0]
	v_pk_add_f32 v[16:17], v[16:17], v[150:151] op_sel_hi:[1,0]
	v_pk_add_f32 v[6:7], v[6:7], v[150:151] op_sel_hi:[1,0]
	v_pk_add_f32 v[8:9], v[8:9], v[150:151] op_sel_hi:[1,0]
	v_rcp_f32_e32 v14, v14
	v_rcp_f32_e32 v15, v15
	v_rcp_f32_e32 v16, v16
	v_rcp_f32_e32 v17, v17
	v_rcp_f32_e32 v6, v6
	v_rcp_f32_e32 v7, v7
	v_rcp_f32_e32 v8, v8
	v_rcp_f32_e32 v9, v9
	v_pk_mul_f32 v[10:11], v[10:11], v[14:15]
	v_pk_mul_f32 v[12:13], v[12:13], v[16:17]
	v_pk_mul_f32 v[2:3], v[2:3], v[6:7]
	v_pk_mul_f32 v[4:5], v[4:5], v[8:9]
	v_cvt_pk_bf16_f32 v236, v10, v11
	v_cvt_pk_bf16_f32 v237, v12, v13
	v_cvt_pk_bf16_f32 v238, v2, v3
	v_cvt_pk_bf16_f32 v239, v4, v5
	global_store_dwordx4 v[252:253], v[236:239], off nt
	s_mov_b64 s[6:7], -1
	s_andn2_b64 vcc, exec, s[12:13]
	s_cbranch_vccnz .LBB0_300
	s_andn2_b64 vcc, exec, s[2:3]
	s_cbranch_vccnz .LBB0_299
	s_barrier
	s_branch .LBB0_299

; __device__ __forceinline__ void attn_unit(KArg P, int L, int b, int nb, int kvh, LAS unsigned char* lds) {
;     ...
;         mx = fmaxf(mx, __shfl_xor(mx, 16)); mx = fmaxf(mx, __shfl_xor(mx, 32));
;         float sum = 0.f;
; #pragma unroll
;         for (int tt = 0; tt < 10; ++tt)
; #pragma unroll
;             for (int r = 0; r < 4; ++r) { const float p = (sc[tt][r] > -1e29f) ? __expf(sc[tt][r] - mx) : 0.f; sc[tt][r] = p; sum += p; }
;         sum += __shfl_xor(sum, 16); sum += __shfl_xor(sum, 32);
.LBB0_583:
	ds_bpermute_b32 v146, v180, v187
	v_max_f32_e32 v147, v187, v187
	s_waitcnt lgkmcnt(0)
	v_max_f32_e32 v146, v146, v146
	v_max_f32_e32 v146, v147, v146
	ds_bpermute_b32 v147, v181, v146
	s_waitcnt lgkmcnt(0)
	v_max_f32_e32 v147, v147, v147
	v_max_f32_e32 v187, v146, v147
	v_sub_f32_e32 v146, v221, v187
	v_mul_f32_e32 v146, 0x3fb8aa3b, v146
	v_sub_f32_e32 v147, v220, v187
	v_exp_f32_e32 v146, v146
	v_mul_f32_e32 v147, 0x3fb8aa3b, v147
	v_exp_f32_e32 v147, v147
	v_sub_f32_e32 v163, v189, v187
	s_nop 0
	v_add_f32_e32 v148, 0, v146
	v_mul_f32_e32 v163, 0x3fb8aa3b, v163
	s_nop 0
	v_add_f32_e32 v150, v147, v148
	v_sub_f32_e32 v148, v219, v187
	v_mul_f32_e32 v148, 0x3fb8aa3b, v148
	v_exp_f32_e32 v148, v148
	v_exp_f32_e32 v163, v163
	v_sub_f32_e32 v164, v199, v187
	s_nop 0
	v_add_f32_e32 v153, v148, v150
	v_sub_f32_e32 v150, v218, v187
	v_mul_f32_e32 v150, 0x3fb8aa3b, v150
	v_exp_f32_e32 v150, v150
	v_mul_f32_e32 v164, 0x3fb8aa3b, v164
	v_sub_f32_e32 v165, v198, v187
	s_nop 0
	v_add_f32_e32 v162, v150, v153
	v_sub_f32_e32 v153, v217, v187
	v_mul_f32_e32 v153, 0x3fb8aa3b, v153
	v_exp_f32_e32 v153, v153
	v_exp_f32_e32 v164, v164
	v_mul_f32_e32 v165, 0x3fb8aa3b, v165
	s_nop 0
	v_add_f32_e32 v162, v153, v162
	v_sub_f32_e32 v168, v194, v187
	v_mov_b32_e32 v189, v163
	v_sub_f32_e32 v163, v192, v187
	v_mul_f32_e32 v163, 0x3fb8aa3b, v163
	v_exp_f32_e32 v163, v163
	v_add_f32_e32 v162, v189, v162
	v_exp_f32_e32 v165, v165
	v_mov_b32_e32 v192, v163
	v_sub_f32_e32 v163, v196, v187
	v_mul_f32_e32 v163, 0x3fb8aa3b, v163
	v_exp_f32_e32 v163, v163
	v_add_f32_e32 v162, v192, v162
	v_mul_f32_e32 v168, 0x3fb8aa3b, v168
	v_mov_b32_e32 v196, v163
	v_sub_f32_e32 v163, v191, v187
	v_mul_f32_e32 v163, 0x3fb8aa3b, v163
	v_exp_f32_e32 v163, v163
	v_add_f32_e32 v162, v196, v162
	v_sub_f32_e32 v169, v193, v187
	v_mov_b32_e32 v191, v163
	v_sub_f32_e32 v163, v195, v187
	v_mul_f32_e32 v163, 0x3fb8aa3b, v163
	v_exp_f32_e32 v163, v163
	v_add_f32_e32 v162, v191, v162
	v_exp_f32_e32 v168, v168
	v_mov_b32_e32 v195, v163
	v_sub_f32_e32 v163, v197, v187
	v_mul_f32_e32 v163, 0x3fb8aa3b, v163
	v_exp_f32_e32 v163, v163
	v_add_f32_e32 v162, v195, v162
	v_mul_f32_e32 v169, 0x3fb8aa3b, v169
	v_mov_b32_e32 v197, v163
	v_sub_f32_e32 v163, v201, v187
	v_mul_f32_e32 v163, 0x3fb8aa3b, v163
	v_exp_f32_e32 v163, v163
	v_add_f32_e32 v162, v197, v162
	v_sub_f32_e32 v170, v190, v187
	v_mov_b32_e32 v201, v163
	v_sub_f32_e32 v163, v202, v187
	v_mul_f32_e32 v163, 0x3fb8aa3b, v163
	v_exp_f32_e32 v163, v163
	v_add_f32_e32 v162, v201, v162
	v_exp_f32_e32 v169, v169
	v_mov_b32_e32 v202, v163
	v_sub_f32_e32 v163, v204, v187
	v_mul_f32_e32 v163, 0x3fb8aa3b, v163
	v_exp_f32_e32 v163, v163
	v_add_f32_e32 v162, v202, v162
	v_mul_f32_e32 v170, 0x3fb8aa3b, v170
	v_mov_b32_e32 v204, v163
	v_sub_f32_e32 v163, v207, v187
	v_mul_f32_e32 v163, 0x3fb8aa3b, v163
	v_exp_f32_e32 v163, v163
	v_add_f32_e32 v162, v204, v162
	v_sub_f32_e32 v171, v188, v187
	v_mov_b32_e32 v207, v163
	v_sub_f32_e32 v163, v211, v187
	v_mul_f32_e32 v163, 0x3fb8aa3b, v163
	v_exp_f32_e32 v163, v163
	v_add_f32_e32 v162, v207, v162
	v_exp_f32_e32 v170, v170
	v_mov_b32_e32 v211, v163
	v_sub_f32_e32 v163, v205, v187
	v_mul_f32_e32 v163, 0x3fb8aa3b, v163
	v_exp_f32_e32 v163, v163
	v_add_f32_e32 v162, v211, v162
	v_mul_f32_e32 v171, 0x3fb8aa3b, v171
	v_mov_b32_e32 v205, v163
	v_sub_f32_e32 v163, v210, v187
	v_mul_f32_e32 v163, 0x3fb8aa3b, v163
	v_exp_f32_e32 v163, v163
	v_add_f32_e32 v162, v205, v162
	v_sub_f32_e32 v172, v186, v187
	v_mov_b32_e32 v210, v163
	v_sub_f32_e32 v163, v213, v187
	v_mul_f32_e32 v163, 0x3fb8aa3b, v163
	v_exp_f32_e32 v163, v163
	v_add_f32_e32 v162, v210, v162
	v_exp_f32_e32 v171, v171
	v_mov_b32_e32 v213, v163
	v_sub_f32_e32 v163, v215, v187
	v_mul_f32_e32 v163, 0x3fb8aa3b, v163
	v_exp_f32_e32 v163, v163
	v_add_f32_e32 v162, v213, v162
	v_mul_f32_e32 v172, 0x3fb8aa3b, v172
	v_mov_b32_e32 v215, v163
	v_sub_f32_e32 v163, v216, v187
	v_mul_f32_e32 v163, 0x3fb8aa3b, v163
	v_exp_f32_e32 v163, v163
	v_sub_f32_e32 v173, v185, v187
	v_add_f32_e32 v162, v215, v162
	v_mov_b32_e32 v216, v163
	v_sub_f32_e32 v163, v214, v187
	v_mul_f32_e32 v163, 0x3fb8aa3b, v163
	v_exp_f32_e32 v163, v163
	v_exp_f32_e32 v172, v172
	v_mul_f32_e32 v173, 0x3fb8aa3b, v173
	v_mov_b32_e32 v214, v163
	v_sub_f32_e32 v163, v212, v187
	v_mul_f32_e32 v163, 0x3fb8aa3b, v163
	v_exp_f32_e32 v163, v163
	v_sub_f32_e32 v174, v184, v187
	v_add_f32_e32 v162, v216, v162
	v_mov_b32_e32 v212, v163
	v_sub_f32_e32 v163, v209, v187
	v_mul_f32_e32 v163, 0x3fb8aa3b, v163
	v_exp_f32_e32 v163, v163
	v_exp_f32_e32 v173, v173
	v_mul_f32_e32 v174, 0x3fb8aa3b, v174
	v_mov_b32_e32 v209, v163
	v_sub_f32_e32 v163, v208, v187
	v_mul_f32_e32 v163, 0x3fb8aa3b, v163
	v_exp_f32_e32 v163, v163
	v_add_f32_e32 v162, v214, v162
	v_exp_f32_e32 v174, v174
	v_mov_b32_e32 v208, v163
	v_sub_f32_e32 v163, v206, v187
	v_mul_f32_e32 v163, 0x3fb8aa3b, v163
	v_exp_f32_e32 v163, v163
	v_add_f32_e32 v162, v212, v162
	v_add_f32_e32 v162, v209, v162
	v_mov_b32_e32 v206, v163
	v_sub_f32_e32 v163, v203, v187
	v_mul_f32_e32 v163, 0x3fb8aa3b, v163
	v_exp_f32_e32 v163, v163
	v_add_f32_e32 v162, v208, v162
	v_add_f32_e32 v162, v206, v162
	v_mov_b32_e32 v203, v163
	v_sub_f32_e32 v163, v200, v187
	v_mul_f32_e32 v163, 0x3fb8aa3b, v163
	v_exp_f32_e32 v163, v163
	v_add_f32_e32 v162, v203, v162
	v_cvt_pk_bf16_f32 v146, v146, v147
	s_nop 0
	v_add_f32_e32 v162, v163, v162
	v_cvt_pk_bf16_f32 v147, v148, v150
	s_nop 0
	v_add_f32_e32 v162, v164, v162
	v_cvt_pk_bf16_f32 v148, v153, v189
	s_nop 0
	v_add_f32_e32 v162, v165, v162
	v_cvt_pk_bf16_f32 v189, v197, v201
	s_nop 0
	v_add_f32_e32 v162, v168, v162
	s_nop 0
	s_nop 0
	v_add_f32_e32 v162, v169, v162
	v_cvt_pk_bf16_f32 v190, v202, v204
	s_nop 0
	v_add_f32_e32 v162, v170, v162
	v_cvt_pk_bf16_f32 v188, v191, v195
	s_nop 0
	v_add_f32_e32 v162, v171, v162
	v_cvt_pk_bf16_f32 v191, v207, v211
	s_nop 0
	v_add_f32_e32 v162, v172, v162
	s_nop 0
	s_nop 0
	v_add_f32_e32 v162, v173, v162
	s_nop 0
	s_nop 0
	v_sub_f32_e32 v152, v152, v187
	v_mul_f32_e32 v152, 0x3fb8aa3b, v152
	v_exp_f32_e32 v152, v152
	v_add_f32_e32 v162, v174, v162
	v_mov_b32_e32 v175, v152
	v_sub_f32_e32 v151, v151, v187
	v_mul_f32_e32 v151, 0x3fb8aa3b, v151
	v_exp_f32_e32 v151, v151
	v_add_f32_e32 v152, v175, v162
	v_mov_b32_e32 v162, v151
	v_sub_f32_e32 v149, v149, v187
	v_mul_f32_e32 v149, 0x3fb8aa3b, v149
	v_exp_f32_e32 v149, v149
	v_add_f32_e32 v151, v162, v152
	v_mov_b32_e32 v198, v149
	v_add_f32_e32 v149, v198, v151
	ds_bpermute_b32 v151, v180, v149
	s_waitcnt lgkmcnt(0)
; #define LAS __attribute__((address_space(3)))
; __device__ __forceinline__ unsigned cvt_pk_bf16(float lo, float hi) { f32x2_t v = {lo, hi}; bf16x2_t b = __builtin_convertvector(v, bf16x2_t); return __builtin_bit_cast(unsigned, b); }
; #define MFMA16(a, b, c) __builtin_amdgcn_mfma_f32_16x16x32_bf16((a), (b), (c), 0, 0, 0)
; __device__ __forceinline__ void attn_unit(KArg P, int L, int b, int nb, int kvh, LAS unsigned char* lds) {
;     ...
;         sum += __shfl_xor(sum, 16); sum += __shfl_xor(sum, 32);
;         const float inv = 1.0f / (sum + __expf(sink - mx));
;         f32x4 oacc[4];
; #pragma unroll
;         for (int dt = 0; dt < 4; ++dt) oacc[dt] = (f32x4){0.f, 0.f, 0.f, 0.f};
; #pragma unroll
;         for (int u = 0; u < 5; ++u) {
;             v4u pb = (v4u){cvt_pk_bf16(sc[2 * u][0], sc[2 * u][1]), cvt_pk_bf16(sc[2 * u][2], sc[2 * u][3]), cvt_pk_bf16(sc[2 * u + 1][0], sc[2 * u + 1][1]), cvt_pk_bf16(sc[2 * u + 1][2], sc[2 * u + 1][3])};
;             const bf16x8 pfr = __builtin_bit_cast(bf16x8, pb);
; #pragma unroll
;             for (int dt = 0; dt < 4; ++dt) {
;                 const int sw = (dt * 2 + (c >> 3)) & 7;
;                 const LAS unsigned char* vr = lds + AT_VT + (dt * 16 + c) * 528;
;                 const v2u lo = *(const LAS v2u*)(vr + ((((tile0 + 2 * u) * 4 + g) ^ sw) * 8)), hi = *(const LAS v2u*)(vr + ((((tile0 + 2 * u + 1) * 4 + g) ^ sw) * 8));
;                 const v4u av = (v4u){lo.x, lo.y, hi.x, hi.y};
;                 oacc[dt] = MFMA16(__builtin_bit_cast(bf16x8, av), pfr, oacc[dt]); } }
; #pragma unroll
;         for (int dt = 0; dt < 4; ++dt) { const f32x4 o = oacc[dt] * inv; v2u wv; wv.x = cvt_pk_bf16(o[0], o[1]); wv.y = cvt_pk_bf16(o[2], o[3]);
;             *(v2u*)(qrow + dt * 16 + 4 * g) = wv; }
	v_add_f32_e32 v149, v149, v151
	ds_bpermute_b32 v151, v181, v149
	s_waitcnt lgkmcnt(0)
	v_add_f32_e32 v149, v149, v151
	s_waitcnt vmcnt(0)
	v_sub_f32_e32 v151, v183, v187
	v_mul_f32_e32 v151, 0x3fb8aa3b, v151
	v_exp_f32_e32 v151, v151
	s_nop 0
	v_add_f32_e32 v183, v151, v149
	v_cvt_pk_bf16_f32 v149, v192, v196
	s_nop 1
	v_mfma_f32_16x16x32_bf16 v[150:153], v[66:69], v[146:149], 0
	v_mfma_f32_16x16x32_bf16 v[184:187], v[70:73], v[146:149], 0
	v_mfma_f32_16x16x32_bf16 v[218:221], v[74:77], v[146:149], 0
	v_mfma_f32_16x16x32_bf16 v[146:149], v[78:81], v[146:149], 0
	v_mfma_f32_16x16x32_bf16 v[150:153], v[82:85], v[188:191], v[150:153]
	v_mfma_f32_16x16x32_bf16 v[184:187], v[86:89], v[188:191], v[184:187]
	v_mfma_f32_16x16x32_bf16 v[192:195], v[90:93], v[188:191], v[218:221]
	v_mfma_f32_16x16x32_bf16 v[146:149], v[94:97], v[188:191], v[146:149]
	v_cvt_pk_bf16_f32 v188, v205, v210
	v_cvt_pk_bf16_f32 v189, v213, v215
	v_cvt_pk_bf16_f32 v190, v216, v214
	v_cvt_pk_bf16_f32 v191, v212, v209
	s_nop 1
	v_mfma_f32_16x16x32_bf16 v[150:153], v[98:101], v[188:191], v[150:153]
	v_mfma_f32_16x16x32_bf16 v[184:187], v[102:105], v[188:191], v[184:187]
	v_mfma_f32_16x16x32_bf16 v[192:195], v[106:109], v[188:191], v[192:195]
	v_mfma_f32_16x16x32_bf16 v[146:149], v[110:113], v[188:191], v[146:149]
	v_cvt_pk_bf16_f32 v188, v208, v206
	v_cvt_pk_bf16_f32 v189, v203, v163
	v_cvt_pk_bf16_f32 v190, v164, v165
	v_cvt_pk_bf16_f32 v191, v168, v169
	s_nop 1
	v_mfma_f32_16x16x32_bf16 v[150:153], v[114:117], v[188:191], v[150:153]
	v_mfma_f32_16x16x32_bf16 v[184:187], v[118:121], v[188:191], v[184:187]
	v_mfma_f32_16x16x32_bf16 v[192:195], v[122:125], v[188:191], v[192:195]
	v_mfma_f32_16x16x32_bf16 v[146:149], v[126:129], v[188:191], v[146:149]
	v_cvt_pk_bf16_f32 v191, v162, v198
	v_div_scale_f32 v162, s[96:97], v183, v183, 1.0
	v_rcp_f32_e32 v163, v162
	v_cvt_pk_bf16_f32 v188, v170, v171
	v_cvt_pk_bf16_f32 v189, v172, v173
	v_cvt_pk_bf16_f32 v190, v174, v175
	v_fma_f32 v164, -v162, v163, 1.0
	v_fmac_f32_e32 v163, v164, v163
	v_div_scale_f32 v164, vcc, 1.0, v183, 1.0
	v_mul_f32_e32 v165, v164, v163
	v_fma_f32 v168, -v162, v165, v164
	v_mfma_f32_16x16x32_bf16 v[150:153], v[130:133], v[188:191], v[150:153]
	v_fmac_f32_e32 v165, v168, v163
	v_fma_f32 v162, -v162, v165, v164
	v_div_fmas_f32 v162, v162, v163, v165
	v_mfma_f32_16x16x32_bf16 v[184:187], v[134:137], v[188:191], v[184:187]
	v_div_fixup_f32 v162, v162, v183, 1.0
	s_nop 2
	v_pk_mul_f32 v[152:153], v[152:153], v[162:163] op_sel_hi:[1,0]
	v_pk_mul_f32 v[150:151], v[150:151], v[162:163] op_sel_hi:[1,0]
	v_mfma_f32_16x16x32_bf16 v[192:195], v[138:141], v[188:191], v[192:195]
	v_lshl_add_u64 v[170:171], v[158:159], 0, s[10:11]
	v_cvt_pk_bf16_f32 v150, v150, v151
	v_cvt_pk_bf16_f32 v151, v152, v153
	v_mfma_f32_16x16x32_bf16 v[146:149], v[142:145], v[188:191], v[146:149]
	s_add_u32 s10, s10, 0x80
	global_store_dwordx2 v[170:171], v[150:151], off offset:-64
	v_pk_mul_f32 v[150:151], v[186:187], v[162:163] op_sel_hi:[1,0]
	v_pk_mul_f32 v[152:153], v[184:185], v[162:163] op_sel_hi:[1,0]
	s_addc_u32 s11, s11, 0
	v_cvt_pk_bf16_f32 v152, v152, v153
	v_cvt_pk_bf16_f32 v153, v150, v151
	s_add_u32 s8, s8, 4
	global_store_dwordx2 v[170:171], v[152:153], off offset:-32
	v_pk_mul_f32 v[150:151], v[194:195], v[162:163] op_sel_hi:[1,0]
	v_pk_mul_f32 v[152:153], v[192:193], v[162:163] op_sel_hi:[1,0]
	v_pk_mul_f32 v[148:149], v[148:149], v[162:163] op_sel_hi:[1,0]
	v_pk_mul_f32 v[146:147], v[146:147], v[162:163] op_sel_hi:[1,0]
	s_addc_u32 s9, s9, 0
	v_cvt_pk_bf16_f32 v152, v152, v153
	v_cvt_pk_bf16_f32 v153, v150, v151
	v_cvt_pk_bf16_f32 v146, v146, v147
	v_cvt_pk_bf16_f32 v147, v148, v149
	s_cmpk_lg_i32 s10, 0x200
	global_store_dwordx2 v[170:171], v[152:153], off
	global_store_dwordx2 v[170:171], v[146:147], off offset:32
	s_cbranch_scc0 .LBB0_572

; #define LAS __attribute__((address_space(3)))
; __device__ __forceinline__ unsigned cvt_pk_bf16(float lo, float hi) { f32x2_t v = {lo, hi}; bf16x2_t b = __builtin_convertvector(v, bf16x2_t); return __builtin_bit_cast(unsigned, b); }
; __device__ __forceinline__ float sigm(float x) { return __builtin_amdgcn_rcpf(1.0f + __expf(-x)); }
;     __device__ __forceinline__ void operator()(AccRef acc, const pg8::Unit& u, int, int, int, int) const {
;     ...
;             for (int m = 0; m < 4; ++m) {
;                 const int row = row0 + ai * 128 + m * 16; const float rs = ((const LAS float*)((LAS unsigned char*)g_lds + pg8::RSL_OFF))[wid * 128 + ai * 64 + m * 16 + fr];
;                 float o[8];
; #pragma unroll
;                 for (int n = 0; n < 2; ++n)
; #pragma unroll
;                     for (int j = 0; j < 4; ++j) { const float gv = acc[ai][0][m][n][j] * rs, uv = acc[ai][1][m][n][j] * rs; o[n * 4 + j] = gv * sigm(gv) * uv; }
;                 v4u w; w.x = cvt_pk_bf16(o[0], o[1]); w.y = cvt_pk_bf16(o[2], o[3]); w.z = cvt_pk_bf16(o[4], o[5]); w.w = cvt_pk_bf16(o[6], o[7]);
;                 *(v4u*)(O + (size_t)row * DFFP + col0) = w; }
.LBB0_854:
	v_mov_b32_e32 v140, v155
	s_lshl_b32 s11, s30, 7
	v_readfirstlane_b32 s6, v140
	v_and_b32_e32 v141, 15, v140
	s_ashr_i32 s7, s6, 6
	v_or_b32_e32 v142, s1, v141
	s_lshl_b32 s1, s7, 9
	s_ashr_i32 s6, s6, 2
	v_lshl_add_u32 v141, v141, 2, s1
	s_andn2_b32 s6, s6, 63
	v_add_u32_e32 v149, 0x20000, v141
	v_add_u32_e32 v148, s6, v142
	ds_read2_b32 v[240:241], v149 offset1:16
	ds_read2_b32 v[242:243], v149 offset0:32 offset1:48
	ds_read2_b32 v[244:245], v149 offset0:64 offset1:80
	ds_read2_b32 v[246:247], v149 offset0:96 offset1:112
	s_lshl_b32 s18, s7, 5
	v_readlane_b32 s6, v254, 43
	s_and_b32 s18, s18, 0x60
	v_readlane_b32 s7, v254, 44
	s_or_b32 s11, s18, s11
	v_lshrrev_b32_e32 v140, 1, v140
	s_movk_i32 s1, 0x1600
	v_and_or_b32 v140, v140, 24, s11
	v_mov_b32_e32 v150, 1.0
	v_ashrrev_i32_e32 v141, 31, v140
	v_mov_b64_e32 v[142:143], s[6:7]
	v_lshlrev_b64 v[140:141], 1, v[140:141]
	v_mad_i64_i32 v[252:253], s[6:7], v148, s1, v[142:143]
	v_lshl_add_u64 v[252:253], v[252:253], 0, v[140:141]
	s_waitcnt lgkmcnt(0)
	v_mul_f32_e32 v248, 0xbfb8aa3b, v240
	v_mul_f32_e32 v250, v240, v240
	v_pk_mul_f32 v[122:123], v[122:123], v[126:127]
	v_pk_mul_f32 v[124:125], v[124:125], v[128:129]
	v_pk_mul_f32 v[114:115], v[114:115], v[118:119]
	v_pk_mul_f32 v[116:117], v[116:117], v[120:121]
	v_pk_mul_f32 v[126:127], v[126:127], v[248:249] op_sel_hi:[1,0]
	v_pk_mul_f32 v[128:129], v[128:129], v[248:249] op_sel_hi:[1,0]
	v_pk_mul_f32 v[118:119], v[118:119], v[248:249] op_sel_hi:[1,0]
	v_pk_mul_f32 v[120:121], v[120:121], v[248:249] op_sel_hi:[1,0]
	v_exp_f32_e32 v126, v126
	v_exp_f32_e32 v127, v127
	v_exp_f32_e32 v128, v128
	v_exp_f32_e32 v129, v129
	v_exp_f32_e32 v118, v118
	v_exp_f32_e32 v119, v119
	v_exp_f32_e32 v120, v120
	v_exp_f32_e32 v121, v121
	v_pk_mul_f32 v[122:123], v[122:123], v[250:251] op_sel_hi:[1,0]
	v_pk_mul_f32 v[124:125], v[124:125], v[250:251] op_sel_hi:[1,0]
	v_pk_mul_f32 v[114:115], v[114:115], v[250:251] op_sel_hi:[1,0]
	v_pk_mul_f32 v[116:117], v[116:117], v[250:251] op_sel_hi:[1,0]
	v_pk_add_f32 v[126:127], v[126:127], v[150:151] op_sel_hi:[1,0]
	v_pk_add_f32 v[128:129], v[128:129], v[150:151] op_sel_hi:[1,0]
	v_pk_add_f32 v[118:119], v[118:119], v[150:151] op_sel_hi:[1,0]
	v_pk_add_f32 v[120:121], v[120:121], v[150:151] op_sel_hi:[1,0]
	v_rcp_f32_e32 v126, v126
	v_rcp_f32_e32 v127, v127
	v_rcp_f32_e32 v128, v128
	v_rcp_f32_e32 v129, v129
	v_rcp_f32_e32 v118, v118
	v_rcp_f32_e32 v119, v119
	v_rcp_f32_e32 v120, v120
	v_rcp_f32_e32 v121, v121
	v_pk_mul_f32 v[122:123], v[122:123], v[126:127]
	v_pk_mul_f32 v[124:125], v[124:125], v[128:129]
	v_pk_mul_f32 v[114:115], v[114:115], v[118:119]
	v_pk_mul_f32 v[116:117], v[116:117], v[120:121]
	v_cvt_pk_bf16_f32 v232, v122, v123
	v_cvt_pk_bf16_f32 v233, v124, v125
	v_cvt_pk_bf16_f32 v234, v114, v115
	v_cvt_pk_bf16_f32 v235, v116, v117
	global_store_dwordx4 v[252:253], v[232:235], off nt
	v_add_co_u32_e32 v252, vcc, 0x16000, v252
	s_nop 1
	v_addc_co_u32_e32 v253, vcc, 0, v253, vcc
	v_mul_f32_e32 v248, 0xbfb8aa3b, v241
	v_mul_f32_e32 v250, v241, v241
	v_pk_mul_f32 v[106:107], v[106:107], v[110:111]
	v_pk_mul_f32 v[108:109], v[108:109], v[112:113]
	v_pk_mul_f32 v[98:99], v[98:99], v[102:103]
	v_pk_mul_f32 v[100:101], v[100:101], v[104:105]
	v_pk_mul_f32 v[110:111], v[110:111], v[248:249] op_sel_hi:[1,0]
	v_pk_mul_f32 v[112:113], v[112:113], v[248:249] op_sel_hi:[1,0]
	v_pk_mul_f32 v[102:103], v[102:103], v[248:249] op_sel_hi:[1,0]
	v_pk_mul_f32 v[104:105], v[104:105], v[248:249] op_sel_hi:[1,0]
	v_exp_f32_e32 v110, v110
	v_exp_f32_e32 v111, v111
	v_exp_f32_e32 v112, v112
	v_exp_f32_e32 v113, v113
	v_exp_f32_e32 v102, v102
	v_exp_f32_e32 v103, v103
	v_exp_f32_e32 v104, v104
	v_exp_f32_e32 v105, v105
	v_pk_mul_f32 v[106:107], v[106:107], v[250:251] op_sel_hi:[1,0]
	v_pk_mul_f32 v[108:109], v[108:109], v[250:251] op_sel_hi:[1,0]
	v_pk_mul_f32 v[98:99], v[98:99], v[250:251] op_sel_hi:[1,0]
	v_pk_mul_f32 v[100:101], v[100:101], v[250:251] op_sel_hi:[1,0]
	v_pk_add_f32 v[110:111], v[110:111], v[150:151] op_sel_hi:[1,0]
	v_pk_add_f32 v[112:113], v[112:113], v[150:151] op_sel_hi:[1,0]
	v_pk_add_f32 v[102:103], v[102:103], v[150:151] op_sel_hi:[1,0]
	v_pk_add_f32 v[104:105], v[104:105], v[150:151] op_sel_hi:[1,0]
	v_rcp_f32_e32 v110, v110
	v_rcp_f32_e32 v111, v111
	v_rcp_f32_e32 v112, v112
	v_rcp_f32_e32 v113, v113
	v_rcp_f32_e32 v102, v102
	v_rcp_f32_e32 v103, v103
	v_rcp_f32_e32 v104, v104
	v_rcp_f32_e32 v105, v105
	v_pk_mul_f32 v[106:107], v[106:107], v[110:111]
	v_pk_mul_f32 v[108:109], v[108:109], v[112:113]
	v_pk_mul_f32 v[98:99], v[98:99], v[102:103]
	v_pk_mul_f32 v[100:101], v[100:101], v[104:105]
	v_cvt_pk_bf16_f32 v236, v106, v107
	v_cvt_pk_bf16_f32 v237, v108, v109
	v_cvt_pk_bf16_f32 v238, v98, v99
	v_cvt_pk_bf16_f32 v239, v100, v101
	global_store_dwordx4 v[252:253], v[236:239], off nt
	v_add_co_u32_e32 v252, vcc, 0x16000, v252
	s_nop 1
	v_addc_co_u32_e32 v253, vcc, 0, v253, vcc
	v_mul_f32_e32 v248, 0xbfb8aa3b, v242
	v_mul_f32_e32 v250, v242, v242
	v_pk_mul_f32 v[90:91], v[90:91], v[94:95]
	v_pk_mul_f32 v[92:93], v[92:93], v[96:97]
	v_pk_mul_f32 v[82:83], v[82:83], v[86:87]
	v_pk_mul_f32 v[84:85], v[84:85], v[88:89]
	v_pk_mul_f32 v[94:95], v[94:95], v[248:249] op_sel_hi:[1,0]
	v_pk_mul_f32 v[96:97], v[96:97], v[248:249] op_sel_hi:[1,0]
	v_pk_mul_f32 v[86:87], v[86:87], v[248:249] op_sel_hi:[1,0]
	v_pk_mul_f32 v[88:89], v[88:89], v[248:249] op_sel_hi:[1,0]
	v_exp_f32_e32 v94, v94
	v_exp_f32_e32 v95, v95
	v_exp_f32_e32 v96, v96
	v_exp_f32_e32 v97, v97
	v_exp_f32_e32 v86, v86
	v_exp_f32_e32 v87, v87
	v_exp_f32_e32 v88, v88
	v_exp_f32_e32 v89, v89
	v_pk_mul_f32 v[90:91], v[90:91], v[250:251] op_sel_hi:[1,0]
; #define LAS __attribute__((address_space(3)))
; __device__ __forceinline__ unsigned cvt_pk_bf16(float lo, float hi) { f32x2_t v = {lo, hi}; bf16x2_t b = __builtin_convertvector(v, bf16x2_t); return __builtin_bit_cast(unsigned, b); }
; __device__ __forceinline__ float sigm(float x) { return __builtin_amdgcn_rcpf(1.0f + __expf(-x)); }
;     __device__ __forceinline__ void operator()(AccRef acc, const pg8::Unit& u, int, int, int, int) const {
;     ...
;             for (int m = 0; m < 4; ++m) {
;                 const int row = row0 + ai * 128 + m * 16; const float rs = ((const LAS float*)((LAS unsigned char*)g_lds + pg8::RSL_OFF))[wid * 128 + ai * 64 + m * 16 + fr];
;                 float o[8];
; #pragma unroll
;                 for (int n = 0; n < 2; ++n)
; #pragma unroll
;                     for (int j = 0; j < 4; ++j) { const float gv = acc[ai][0][m][n][j] * rs, uv = acc[ai][1][m][n][j] * rs; o[n * 4 + j] = gv * sigm(gv) * uv; }
;                 v4u w; w.x = cvt_pk_bf16(o[0], o[1]); w.y = cvt_pk_bf16(o[2], o[3]); w.z = cvt_pk_bf16(o[4], o[5]); w.w = cvt_pk_bf16(o[6], o[7]);
;                 *(v4u*)(O + (size_t)row * DFFP + col0) = w; }
	v_pk_mul_f32 v[92:93], v[92:93], v[250:251] op_sel_hi:[1,0]
	v_pk_mul_f32 v[82:83], v[82:83], v[250:251] op_sel_hi:[1,0]
	v_pk_mul_f32 v[84:85], v[84:85], v[250:251] op_sel_hi:[1,0]
	v_pk_add_f32 v[94:95], v[94:95], v[150:151] op_sel_hi:[1,0]
	v_pk_add_f32 v[96:97], v[96:97], v[150:151] op_sel_hi:[1,0]
	v_pk_add_f32 v[86:87], v[86:87], v[150:151] op_sel_hi:[1,0]
	v_pk_add_f32 v[88:89], v[88:89], v[150:151] op_sel_hi:[1,0]
	v_rcp_f32_e32 v94, v94
	v_rcp_f32_e32 v95, v95
	v_rcp_f32_e32 v96, v96
	v_rcp_f32_e32 v97, v97
	v_rcp_f32_e32 v86, v86
	v_rcp_f32_e32 v87, v87
	v_rcp_f32_e32 v88, v88
	v_rcp_f32_e32 v89, v89
	v_pk_mul_f32 v[90:91], v[90:91], v[94:95]
	v_pk_mul_f32 v[92:93], v[92:93], v[96:97]
	v_pk_mul_f32 v[82:83], v[82:83], v[86:87]
	v_pk_mul_f32 v[84:85], v[84:85], v[88:89]
	v_cvt_pk_bf16_f32 v232, v90, v91
	v_cvt_pk_bf16_f32 v233, v92, v93
	v_cvt_pk_bf16_f32 v234, v82, v83
	v_cvt_pk_bf16_f32 v235, v84, v85
	global_store_dwordx4 v[252:253], v[232:235], off nt
	v_add_co_u32_e32 v252, vcc, 0x16000, v252
	s_nop 1
	v_addc_co_u32_e32 v253, vcc, 0, v253, vcc
	v_mul_f32_e32 v248, 0xbfb8aa3b, v243
	v_mul_f32_e32 v250, v243, v243
	v_pk_mul_f32 v[74:75], v[74:75], v[78:79]
	v_pk_mul_f32 v[76:77], v[76:77], v[80:81]
	v_pk_mul_f32 v[66:67], v[66:67], v[70:71]
	v_pk_mul_f32 v[68:69], v[68:69], v[72:73]
	v_pk_mul_f32 v[78:79], v[78:79], v[248:249] op_sel_hi:[1,0]
	v_pk_mul_f32 v[80:81], v[80:81], v[248:249] op_sel_hi:[1,0]
	v_pk_mul_f32 v[70:71], v[70:71], v[248:249] op_sel_hi:[1,0]
	v_pk_mul_f32 v[72:73], v[72:73], v[248:249] op_sel_hi:[1,0]
	v_exp_f32_e32 v78, v78
	v_exp_f32_e32 v79, v79
	v_exp_f32_e32 v80, v80
	v_exp_f32_e32 v81, v81
	v_exp_f32_e32 v70, v70
	v_exp_f32_e32 v71, v71
	v_exp_f32_e32 v72, v72
	v_exp_f32_e32 v73, v73
	v_pk_mul_f32 v[74:75], v[74:75], v[250:251] op_sel_hi:[1,0]
	v_pk_mul_f32 v[76:77], v[76:77], v[250:251] op_sel_hi:[1,0]
	v_pk_mul_f32 v[66:67], v[66:67], v[250:251] op_sel_hi:[1,0]
	v_pk_mul_f32 v[68:69], v[68:69], v[250:251] op_sel_hi:[1,0]
	v_pk_add_f32 v[78:79], v[78:79], v[150:151] op_sel_hi:[1,0]
	v_pk_add_f32 v[80:81], v[80:81], v[150:151] op_sel_hi:[1,0]
	v_pk_add_f32 v[70:71], v[70:71], v[150:151] op_sel_hi:[1,0]
	v_pk_add_f32 v[72:73], v[72:73], v[150:151] op_sel_hi:[1,0]
	v_rcp_f32_e32 v78, v78
	v_rcp_f32_e32 v79, v79
	v_rcp_f32_e32 v80, v80
	v_rcp_f32_e32 v81, v81
	v_rcp_f32_e32 v70, v70
	v_rcp_f32_e32 v71, v71
	v_rcp_f32_e32 v72, v72
	v_rcp_f32_e32 v73, v73
	v_pk_mul_f32 v[74:75], v[74:75], v[78:79]
	v_pk_mul_f32 v[76:77], v[76:77], v[80:81]
	v_pk_mul_f32 v[66:67], v[66:67], v[70:71]
	v_pk_mul_f32 v[68:69], v[68:69], v[72:73]
	v_cvt_pk_bf16_f32 v236, v74, v75
	v_cvt_pk_bf16_f32 v237, v76, v77
	v_cvt_pk_bf16_f32 v238, v66, v67
	v_cvt_pk_bf16_f32 v239, v68, v69
	global_store_dwordx4 v[252:253], v[236:239], off nt
	v_add_co_u32_e32 v252, vcc, 0x6e000, v252
	s_nop 1
	v_addc_co_u32_e32 v253, vcc, 0, v253, vcc
	v_mul_f32_e32 v248, 0xbfb8aa3b, v244
	v_mul_f32_e32 v250, v244, v244
	v_pk_mul_f32 v[58:59], v[58:59], v[62:63]
	v_pk_mul_f32 v[60:61], v[60:61], v[64:65]
	v_pk_mul_f32 v[50:51], v[50:51], v[54:55]
	v_pk_mul_f32 v[52:53], v[52:53], v[56:57]
	v_pk_mul_f32 v[62:63], v[62:63], v[248:249] op_sel_hi:[1,0]
	v_pk_mul_f32 v[64:65], v[64:65], v[248:249] op_sel_hi:[1,0]
	v_pk_mul_f32 v[54:55], v[54:55], v[248:249] op_sel_hi:[1,0]
	v_pk_mul_f32 v[56:57], v[56:57], v[248:249] op_sel_hi:[1,0]
	v_exp_f32_e32 v62, v62
	v_exp_f32_e32 v63, v63
	v_exp_f32_e32 v64, v64
	v_exp_f32_e32 v65, v65
	v_exp_f32_e32 v54, v54
	v_exp_f32_e32 v55, v55
	v_exp_f32_e32 v56, v56
	v_exp_f32_e32 v57, v57
	v_pk_mul_f32 v[58:59], v[58:59], v[250:251] op_sel_hi:[1,0]
	v_pk_mul_f32 v[60:61], v[60:61], v[250:251] op_sel_hi:[1,0]
	v_pk_mul_f32 v[50:51], v[50:51], v[250:251] op_sel_hi:[1,0]
	v_pk_mul_f32 v[52:53], v[52:53], v[250:251] op_sel_hi:[1,0]
	v_pk_add_f32 v[62:63], v[62:63], v[150:151] op_sel_hi:[1,0]
	v_pk_add_f32 v[64:65], v[64:65], v[150:151] op_sel_hi:[1,0]
	v_pk_add_f32 v[54:55], v[54:55], v[150:151] op_sel_hi:[1,0]
	v_pk_add_f32 v[56:57], v[56:57], v[150:151] op_sel_hi:[1,0]
	v_rcp_f32_e32 v62, v62
	v_rcp_f32_e32 v63, v63
	v_rcp_f32_e32 v64, v64
	v_rcp_f32_e32 v65, v65
	v_rcp_f32_e32 v54, v54
	v_rcp_f32_e32 v55, v55
	v_rcp_f32_e32 v56, v56
	v_rcp_f32_e32 v57, v57
	v_pk_mul_f32 v[58:59], v[58:59], v[62:63]
	v_pk_mul_f32 v[60:61], v[60:61], v[64:65]
	v_pk_mul_f32 v[50:51], v[50:51], v[54:55]
	v_pk_mul_f32 v[52:53], v[52:53], v[56:57]
	v_cvt_pk_bf16_f32 v232, v58, v59
	v_cvt_pk_bf16_f32 v233, v60, v61
	v_cvt_pk_bf16_f32 v234, v50, v51
	v_cvt_pk_bf16_f32 v235, v52, v53
	global_store_dwordx4 v[252:253], v[232:235], off nt
	v_add_co_u32_e32 v252, vcc, 0x16000, v252
	s_nop 1
	v_addc_co_u32_e32 v253, vcc, 0, v253, vcc
	v_mul_f32_e32 v248, 0xbfb8aa3b, v245
	v_mul_f32_e32 v250, v245, v245
	v_pk_mul_f32 v[42:43], v[42:43], v[46:47]
	v_pk_mul_f32 v[44:45], v[44:45], v[48:49]
	v_pk_mul_f32 v[34:35], v[34:35], v[38:39]
	v_pk_mul_f32 v[36:37], v[36:37], v[40:41]
	v_pk_mul_f32 v[46:47], v[46:47], v[248:249] op_sel_hi:[1,0]
	v_pk_mul_f32 v[48:49], v[48:49], v[248:249] op_sel_hi:[1,0]
; #define LAS __attribute__((address_space(3)))
; __device__ __forceinline__ unsigned cvt_pk_bf16(float lo, float hi) { f32x2_t v = {lo, hi}; bf16x2_t b = __builtin_convertvector(v, bf16x2_t); return __builtin_bit_cast(unsigned, b); }
; __device__ __forceinline__ float sigm(float x) { return __builtin_amdgcn_rcpf(1.0f + __expf(-x)); }
; #define PG8_BAR __builtin_amdgcn_s_barrier()
; template <class Epi, bool ALIGN_EPI>
; __device__ __forceinline__ void gemm_phase(LAS unsigned char* lds, const Gemm g, const StaticOrder& S, const Epi& E) {
;     ...
;         if (!has_next) break;
; #pragma unroll
;         for (int a = 0; a < 2; ++a)
; #pragma unroll
;             for (int b = 0; b < 2; ++b)
; #pragma unroll
;                 for (int m = 0; m < 4; ++m)
; #pragma unroll
;                     for (int n = 0; n < 2; ++n) acc[a][b][m][n] = (f32x4){0.f, 0.f, 0.f, 0.f};
;         cur = nxt; cA = nA; cB = nB; ++ui;
;         if constexpr (ALIGN_EPI) { if (wr == 1) PG8_BAR; }
;     __device__ __forceinline__ void operator()(AccRef acc, const pg8::Unit& u, int, int, int, int) const {
;     ...
;             for (int m = 0; m < 4; ++m) {
;                 const int row = row0 + ai * 128 + m * 16; const float rs = ((const LAS float*)((LAS unsigned char*)g_lds + pg8::RSL_OFF))[wid * 128 + ai * 64 + m * 16 + fr];
;                 float o[8];
; #pragma unroll
;                 for (int n = 0; n < 2; ++n)
; #pragma unroll
;                     for (int j = 0; j < 4; ++j) { const float gv = acc[ai][0][m][n][j] * rs, uv = acc[ai][1][m][n][j] * rs; o[n * 4 + j] = gv * sigm(gv) * uv; }
;                 v4u w; w.x = cvt_pk_bf16(o[0], o[1]); w.y = cvt_pk_bf16(o[2], o[3]); w.z = cvt_pk_bf16(o[4], o[5]); w.w = cvt_pk_bf16(o[6], o[7]);
;                 *(v4u*)(O + (size_t)row * DFFP + col0) = w; }
	v_pk_mul_f32 v[38:39], v[38:39], v[248:249] op_sel_hi:[1,0]
	v_pk_mul_f32 v[40:41], v[40:41], v[248:249] op_sel_hi:[1,0]
	v_exp_f32_e32 v46, v46
	v_exp_f32_e32 v47, v47
	v_exp_f32_e32 v48, v48
	v_exp_f32_e32 v49, v49
	v_exp_f32_e32 v38, v38
	v_exp_f32_e32 v39, v39
	v_exp_f32_e32 v40, v40
	v_exp_f32_e32 v41, v41
	v_pk_mul_f32 v[42:43], v[42:43], v[250:251] op_sel_hi:[1,0]
	v_pk_mul_f32 v[44:45], v[44:45], v[250:251] op_sel_hi:[1,0]
	v_pk_mul_f32 v[34:35], v[34:35], v[250:251] op_sel_hi:[1,0]
	v_pk_mul_f32 v[36:37], v[36:37], v[250:251] op_sel_hi:[1,0]
	v_pk_add_f32 v[46:47], v[46:47], v[150:151] op_sel_hi:[1,0]
	v_pk_add_f32 v[48:49], v[48:49], v[150:151] op_sel_hi:[1,0]
	v_pk_add_f32 v[38:39], v[38:39], v[150:151] op_sel_hi:[1,0]
	v_pk_add_f32 v[40:41], v[40:41], v[150:151] op_sel_hi:[1,0]
	v_rcp_f32_e32 v46, v46
	v_rcp_f32_e32 v47, v47
	v_rcp_f32_e32 v48, v48
	v_rcp_f32_e32 v49, v49
	v_rcp_f32_e32 v38, v38
	v_rcp_f32_e32 v39, v39
	v_rcp_f32_e32 v40, v40
	v_rcp_f32_e32 v41, v41
	v_pk_mul_f32 v[42:43], v[42:43], v[46:47]
	v_pk_mul_f32 v[44:45], v[44:45], v[48:49]
	v_pk_mul_f32 v[34:35], v[34:35], v[38:39]
	v_pk_mul_f32 v[36:37], v[36:37], v[40:41]
	v_cvt_pk_bf16_f32 v236, v42, v43
	v_cvt_pk_bf16_f32 v237, v44, v45
	v_cvt_pk_bf16_f32 v238, v34, v35
	v_cvt_pk_bf16_f32 v239, v36, v37
	global_store_dwordx4 v[252:253], v[236:239], off nt
	v_add_co_u32_e32 v252, vcc, 0x16000, v252
	s_nop 1
	v_addc_co_u32_e32 v253, vcc, 0, v253, vcc
	v_mul_f32_e32 v248, 0xbfb8aa3b, v246
	v_mul_f32_e32 v250, v246, v246
	v_pk_mul_f32 v[26:27], v[26:27], v[30:31]
	v_pk_mul_f32 v[28:29], v[28:29], v[32:33]
	v_pk_mul_f32 v[18:19], v[18:19], v[22:23]
	v_pk_mul_f32 v[20:21], v[20:21], v[24:25]
	v_pk_mul_f32 v[30:31], v[30:31], v[248:249] op_sel_hi:[1,0]
	v_pk_mul_f32 v[32:33], v[32:33], v[248:249] op_sel_hi:[1,0]
	v_pk_mul_f32 v[22:23], v[22:23], v[248:249] op_sel_hi:[1,0]
	v_pk_mul_f32 v[24:25], v[24:25], v[248:249] op_sel_hi:[1,0]
	v_exp_f32_e32 v30, v30
	v_exp_f32_e32 v31, v31
	v_exp_f32_e32 v32, v32
	v_exp_f32_e32 v33, v33
	v_exp_f32_e32 v22, v22
	v_exp_f32_e32 v23, v23
	v_exp_f32_e32 v24, v24
	v_exp_f32_e32 v25, v25
	v_pk_mul_f32 v[26:27], v[26:27], v[250:251] op_sel_hi:[1,0]
	v_pk_mul_f32 v[28:29], v[28:29], v[250:251] op_sel_hi:[1,0]
	v_pk_mul_f32 v[18:19], v[18:19], v[250:251] op_sel_hi:[1,0]
	v_pk_mul_f32 v[20:21], v[20:21], v[250:251] op_sel_hi:[1,0]
	v_pk_add_f32 v[30:31], v[30:31], v[150:151] op_sel_hi:[1,0]
	v_pk_add_f32 v[32:33], v[32:33], v[150:151] op_sel_hi:[1,0]
	v_pk_add_f32 v[22:23], v[22:23], v[150:151] op_sel_hi:[1,0]
	v_pk_add_f32 v[24:25], v[24:25], v[150:151] op_sel_hi:[1,0]
	v_rcp_f32_e32 v30, v30
	v_rcp_f32_e32 v31, v31
	v_rcp_f32_e32 v32, v32
	v_rcp_f32_e32 v33, v33
	v_rcp_f32_e32 v22, v22
	v_rcp_f32_e32 v23, v23
	v_rcp_f32_e32 v24, v24
	v_rcp_f32_e32 v25, v25
	v_pk_mul_f32 v[26:27], v[26:27], v[30:31]
	v_pk_mul_f32 v[28:29], v[28:29], v[32:33]
	v_pk_mul_f32 v[18:19], v[18:19], v[22:23]
	v_pk_mul_f32 v[20:21], v[20:21], v[24:25]
	v_cvt_pk_bf16_f32 v232, v26, v27
	v_cvt_pk_bf16_f32 v233, v28, v29
	v_cvt_pk_bf16_f32 v234, v18, v19
	v_cvt_pk_bf16_f32 v235, v20, v21
	global_store_dwordx4 v[252:253], v[232:235], off nt
	v_add_co_u32_e32 v252, vcc, 0x16000, v252
	s_nop 1
	v_addc_co_u32_e32 v253, vcc, 0, v253, vcc
	v_mul_f32_e32 v248, 0xbfb8aa3b, v247
	v_mul_f32_e32 v250, v247, v247
	v_pk_mul_f32 v[10:11], v[10:11], v[14:15]
	v_pk_mul_f32 v[12:13], v[12:13], v[16:17]
	v_pk_mul_f32 v[2:3], v[2:3], v[6:7]
	v_pk_mul_f32 v[4:5], v[4:5], v[8:9]
	v_pk_mul_f32 v[14:15], v[14:15], v[248:249] op_sel_hi:[1,0]
	v_pk_mul_f32 v[16:17], v[16:17], v[248:249] op_sel_hi:[1,0]
	v_pk_mul_f32 v[6:7], v[6:7], v[248:249] op_sel_hi:[1,0]
	v_pk_mul_f32 v[8:9], v[8:9], v[248:249] op_sel_hi:[1,0]
	v_exp_f32_e32 v14, v14
	v_exp_f32_e32 v15, v15
	v_exp_f32_e32 v16, v16
	v_exp_f32_e32 v17, v17
	v_exp_f32_e32 v6, v6
	v_exp_f32_e32 v7, v7
	v_exp_f32_e32 v8, v8
	v_exp_f32_e32 v9, v9
	v_pk_mul_f32 v[10:11], v[10:11], v[250:251] op_sel_hi:[1,0]
	v_pk_mul_f32 v[12:13], v[12:13], v[250:251] op_sel_hi:[1,0]
	v_pk_mul_f32 v[2:3], v[2:3], v[250:251] op_sel_hi:[1,0]
	v_pk_mul_f32 v[4:5], v[4:5], v[250:251] op_sel_hi:[1,0]
	v_pk_add_f32 v[14:15], v[14:15], v[150:151] op_sel_hi:[1,0]
	v_pk_add_f32 v[16:17], v[16:17], v[150:151] op_sel_hi:[1,0]
	v_pk_add_f32 v[6:7], v[6:7], v[150:151] op_sel_hi:[1,0]
	v_pk_add_f32 v[8:9], v[8:9], v[150:151] op_sel_hi:[1,0]
	v_rcp_f32_e32 v14, v14
	v_rcp_f32_e32 v15, v15
	v_rcp_f32_e32 v16, v16
	v_rcp_f32_e32 v17, v17
	v_rcp_f32_e32 v6, v6
	v_rcp_f32_e32 v7, v7
	v_rcp_f32_e32 v8, v8
	v_rcp_f32_e32 v9, v9
	v_pk_mul_f32 v[10:11], v[10:11], v[14:15]
	v_pk_mul_f32 v[12:13], v[12:13], v[16:17]
	v_pk_mul_f32 v[2:3], v[2:3], v[6:7]
	v_pk_mul_f32 v[4:5], v[4:5], v[8:9]
	v_cvt_pk_bf16_f32 v236, v10, v11
	v_cvt_pk_bf16_f32 v237, v12, v13
	v_cvt_pk_bf16_f32 v238, v2, v3
	v_cvt_pk_bf16_f32 v239, v4, v5
	global_store_dwordx4 v[252:253], v[236:239], off nt
	s_mov_b64 s[6:7], -1
	s_andn2_b64 vcc, exec, s[12:13]
	s_cbranch_vccnz .LBB0_845
	s_andn2_b64 vcc, exec, s[2:3]
	s_cbranch_vccnz .LBB0_844
	s_barrier
	s_branch .LBB0_844

; __device__ __forceinline__ unsigned cvt_pk_bf16(float lo, float hi) { f32x2_t v = {lo, hi}; bf16x2_t b = __builtin_convertvector(v, bf16x2_t); return __builtin_bit_cast(unsigned, b); }
; __device__ __forceinline__ float wave_sum_dpp(float v) { return __int_as_float(__builtin_amdgcn_readlane(__float_as_int(wave_scan_add(v)), 63)); }
; __device__ __forceinline__ void phase_convert(KArg P, int L, LAS unsigned char* lds, int vcu, int G) {
;     ...
;         for (int m0 = gw; m0 < MROWS; m0 += 2 * NGW) { f32x4 v[2][4];
; #pragma unroll
;             for (int k = 0; k < 2; ++k) { const int m = (m0 + k * NGW < MROWS) ? m0 + k * NGW : m0;
; #pragma unroll
;                 for (int j = 0; j < 4; ++j) v[k][j] = *(const f32x4*)(x + (size_t)m * DM + j * 256 + lane * 4); }
; #pragma unroll
;             for (int k = 0; k < 2; ++k) { const int m = m0 + k * NGW; if (m >= MROWS) continue; float ss = 0.f;
; #pragma unroll
;                 for (int j = 0; j < 4; ++j) { const f32x4 t = v[k][j];
;                     v2u w; w.x = cvt_pk_bf16(t[0], t[1]); w.y = cvt_pk_bf16(t[2], t[3]); *(v2u*)(hb2 + (size_t)m * DM + j * 256 + lane * 4) = w;
;                     ss += (t[0] * t[0] + t[1] * t[1]) + (t[2] * t[2] + t[3] * t[3]); }
;                 ss = wave_sum_dpp(ss); if (lane < 16) rowss[(size_t)m * 16 + lane] = (lane == 0) ? ss : 0.f; } }
.LBB0_1250:
	v_ashrrev_i32_e32 v67, 31, v66
	s_waitcnt vmcnt(4)
	v_lshlrev_b64 v[2:3], 12, v[66:67]
	v_lshl_add_u64 v[2:3], v[20:21], 0, v[2:3]
	global_load_dwordx4 v[26:29], v[2:3], off nt
	global_load_dwordx4 v[30:33], v[2:3], off offset:1024 nt
	global_load_dwordx4 v[34:37], v[2:3], off offset:2048 nt
	global_load_dwordx4 v[38:41], v[2:3], off offset:3072 nt
	v_add_u32_e32 v24, s4, v66
	s_mov_b32 s8, 0x8000
	v_cmp_gt_i32_e64 s[8:9], s8, v24
	v_mov_b32_e32 v0, v1
	v_lshlrev_b64 v[42:43], 11, v[66:67]
	v_cndmask_b32_e64 v2, v66, v24, s[8:9]
	v_ashrrev_i32_e32 v3, 31, v2
	v_lshlrev_b64 v[2:3], 12, v[2:3]
	v_lshl_add_u64 v[2:3], v[20:21], 0, v[2:3]
	global_load_dwordx4 v[14:17], v[2:3], off nt
	global_load_dwordx4 v[10:13], v[2:3], off offset:1024 nt
	global_load_dwordx4 v[6:9], v[2:3], off offset:2048 nt
	s_nop 0
	global_load_dwordx4 v[2:5], v[2:3], off offset:3072 nt
	v_lshl_add_u64 v[42:43], v[18:19], 0, v[42:43]
	s_waitcnt vmcnt(7)
	v_cvt_pk_bf16_f32 v44, v26, v27
	v_cvt_pk_bf16_f32 v45, v28, v29
	v_mul_f32_e32 v25, v27, v27
	v_mul_f32_e32 v27, v29, v29
	s_waitcnt vmcnt(6)
	v_cvt_pk_bf16_f32 v46, v30, v31
	v_mul_f32_e32 v29, v31, v31
	v_mul_f32_e32 v31, v33, v33
	v_cvt_pk_bf16_f32 v47, v32, v33
	s_waitcnt vmcnt(5)
	v_cvt_pk_bf16_f32 v48, v34, v35
	v_mul_f32_e32 v33, v35, v35
	v_mul_f32_e32 v35, v37, v37
	v_fmac_f32_e32 v25, v26, v26
	v_fmac_f32_e32 v27, v28, v28
	v_fmac_f32_e32 v29, v30, v30
	v_fmac_f32_e32 v31, v32, v32
	v_cvt_pk_bf16_f32 v49, v36, v37
	s_waitcnt vmcnt(4)
	v_cvt_pk_bf16_f32 v50, v38, v39
	v_mul_f32_e32 v37, v39, v39
	v_mul_f32_e32 v39, v41, v41
	v_fmac_f32_e32 v33, v34, v34
	v_fmac_f32_e32 v35, v36, v36
	v_add_f32_e32 v25, v25, v27
	v_add_f32_e32 v26, v29, v31
	v_fmac_f32_e32 v37, v38, v38
	v_fmac_f32_e32 v39, v40, v40
	v_add_f32_e32 v27, v33, v35
	v_add_f32_e32 v25, v26, v25
	v_add_f32_e32 v28, v37, v39
	v_add_f32_e32 v25, v27, v25
	v_add_f32_e32 v25, v28, v25
	v_cvt_pk_bf16_f32 v51, v40, v41
	global_store_dwordx2 v[42:43], v[44:45], off
	v_add_f32_dpp v25, v25, v25 row_shr:1 row_mask:0xf bank_mask:0xf bound_ctrl:1
	global_store_dwordx2 v[42:43], v[46:47], off offset:512
	global_store_dwordx2 v[42:43], v[48:49], off offset:1024
	v_add_f32_dpp v25, v25, v25 row_shr:2 row_mask:0xf bank_mask:0xf bound_ctrl:1
	global_store_dwordx2 v[42:43], v[50:51], off offset:1536
	s_nop 0
	v_add_f32_dpp v25, v25, v25 row_shr:4 row_mask:0xf bank_mask:0xf bound_ctrl:1
	s_nop 1
	v_add_f32_dpp v25, v25, v25 row_shr:8 row_mask:0xf bank_mask:0xf bound_ctrl:1
	s_nop 1
	v_mov_b32_dpp v0, v25 row_bcast:15 row_mask:0xa bank_mask:0xf
	v_add_f32_e32 v0, v25, v0
	v_mov_b32_e32 v25, v1
	s_nop 1
	v_mov_b32_dpp v25, v0 row_bcast:31 row_mask:0xc bank_mask:0xf
	v_add_f32_e32 v0, v0, v25
	s_nop 0
	v_readlane_b32 s10, v0, 63
	s_and_saveexec_b64 s[8:9], vcc
	s_cbranch_execz .LBB0_1252
	v_mov_b32_e32 v0, s10
	v_lshlrev_b64 v[26:27], 6, v[66:67]
	v_cndmask_b32_e64 v0, 0, v0, s[6:7]
	v_lshl_add_u64 v[26:27], v[22:23], 0, v[26:27]
	global_store_dword v[26:27], v0, off
